# attention P.V: key-block-1 row-sum adds moved out of the exp gaps into the gaps of the last eight MFMAs (same f32 sum, different association)
# speedup vs baseline: 1.0107x; 1.0003x over previous
.LBB0_1010:
	s_lshl_b32 s90, s90, 14
	s_add_i32 s90, s90, 0x12000
	v_add_u32_e32 v2, s90, v163
	ds_read_b128 v[222:225], v2
	ds_read_b128 v[226:229], v2 offset:4096
	ds_read_b128 v[230:233], v2 offset:8192
	ds_read_b128 v[234:237], v2 offset:12288
	v_add_u32_e32 v2, s90, v171
	ds_read_b128 v[238:241], v2
	ds_read_b128 v[242:245], v2 offset:4096
	ds_read_b128 v[246:249], v2 offset:8192
	ds_read_b128 v[250:253], v2 offset:12288
	v_exp_f32_e32 v2, v98
	v_exp_f32_e32 v4, v99
	v_exp_f32_e32 v5, v100
	v_exp_f32_e32 v6, v101
	v_add_f32_e32 v7, 0, v2
	v_exp_f32_e32 v8, v102
	v_add_f32_e32 v7, v4, v7
	v_exp_f32_e32 v9, v103
	v_add_f32_e32 v7, v5, v7
	v_exp_f32_e32 v10, v104
	v_add_f32_e32 v7, v6, v7
	v_exp_f32_e32 v11, v105
	v_add_f32_e32 v7, v8, v7
	v_exp_f32_e32 v16, v106
	v_add_f32_e32 v7, v9, v7
	v_exp_f32_e32 v106, v107
	v_add_f32_e32 v7, v10, v7
	v_exp_f32_e32 v107, v108
	v_add_f32_e32 v7, v11, v7
	v_exp_f32_e32 v108, v109
	v_add_f32_e32 v7, v16, v7
	v_exp_f32_e32 v109, v110
	v_add_f32_e32 v7, v106, v7
	v_exp_f32_e32 v110, v111
	v_add_f32_e32 v7, v107, v7
	v_exp_f32_e32 v111, v112
	v_add_f32_e32 v7, v108, v7
	v_exp_f32_e32 v112, v113
	v_add_f32_e32 v7, v109, v7
	v_add_f32_e32 v7, v110, v7
	v_add_f32_e32 v7, v111, v7
	v_cvt_pk_bf16_f32 v4, v2, v4
	v_add_f32_e32 v17, v112, v7
	v_cvt_pk_bf16_f32 v5, v5, v6
	v_cvt_pk_bf16_f32 v6, v8, v9
	v_cvt_pk_bf16_f32 v7, v10, v11
	v_cvt_pk_bf16_f32 v106, v16, v106
	v_cvt_pk_bf16_f32 v107, v107, v108
	v_cvt_pk_bf16_f32 v108, v109, v110
	v_cvt_pk_bf16_f32 v109, v111, v112
	s_setprio 2
	s_waitcnt lgkmcnt(7)
	v_mfma_f32_32x32x16_bf16 v[66:81], v[222:225], v[4:7], v[66:81]
	v_exp_f32_e32 v2, v82
	v_exp_f32_e32 v185, v83
	s_nop 0
	v_add_f32_e32 v205, v2, v17
	s_waitcnt lgkmcnt(6)
	v_mfma_f32_32x32x16_bf16 v[50:65], v[226:229], v[4:7], v[50:65]
	v_exp_f32_e32 v198, v84
	v_exp_f32_e32 v16, v85
	s_waitcnt lgkmcnt(5)
	v_mfma_f32_32x32x16_bf16 v[34:49], v[230:233], v[4:7], v[34:49]
	v_exp_f32_e32 v17, v86
	v_exp_f32_e32 v199, v87
	s_waitcnt lgkmcnt(4)
	v_mfma_f32_32x32x16_bf16 v[18:33], v[234:237], v[4:7], v[18:33]
	v_exp_f32_e32 v202, v88
	v_exp_f32_e32 v200, v89
	v_add_u32_e32 v82, s90, v172
	ds_read_b128 v[4:7], v82
	ds_read_b128 v[8:11], v82 offset:4096
	ds_read_b128 v[12:15], v82 offset:8192
	ds_read_b128 v[82:85], v82 offset:12288
	s_waitcnt lgkmcnt(7)
	v_mfma_f32_32x32x16_bf16 v[66:81], v[238:241], v[106:109], v[66:81]
	v_exp_f32_e32 v201, v90
	v_exp_f32_e32 v203, v91
	s_waitcnt lgkmcnt(6)
	v_mfma_f32_32x32x16_bf16 v[50:65], v[242:245], v[106:109], v[50:65]
	v_exp_f32_e32 v206, v92
	v_exp_f32_e32 v204, v93
	s_waitcnt lgkmcnt(5)
	v_mfma_f32_32x32x16_bf16 v[34:49], v[246:249], v[106:109], v[34:49]
	v_exp_f32_e32 v186, v94
	v_exp_f32_e32 v187, v95
	s_waitcnt lgkmcnt(4)
	v_mfma_f32_32x32x16_bf16 v[18:33], v[250:253], v[106:109], v[18:33]
	v_exp_f32_e32 v112, v96
	v_exp_f32_e32 v110, v97
	v_add_u32_e32 v98, s90, v173
	ds_read_b128 v[86:89], v98
	ds_read_b128 v[90:93], v98 offset:4096
	ds_read_b128 v[94:97], v98 offset:8192
	ds_read_b128 v[98:101], v98 offset:12288
	v_cvt_pk_bf16_f32 v102, v2, v185
	v_cvt_pk_bf16_f32 v103, v198, v16
	v_cvt_pk_bf16_f32 v104, v17, v199
	v_cvt_pk_bf16_f32 v105, v202, v200
	v_cvt_pk_bf16_f32 v106, v201, v203
	v_cvt_pk_bf16_f32 v107, v206, v204
	v_cvt_pk_bf16_f32 v108, v186, v187
	v_cvt_pk_bf16_f32 v109, v112, v110
	s_waitcnt lgkmcnt(7)
	v_mfma_f32_32x32x16_bf16 v[66:81], v[4:7], v[102:105], v[66:81]
	v_add_f32_e32 v185, v185, v198
	v_add_f32_e32 v16, v16, v17
	s_waitcnt lgkmcnt(6)
	v_mfma_f32_32x32x16_bf16 v[50:65], v[8:11], v[102:105], v[50:65]
	v_add_f32_e32 v199, v199, v202
	v_add_f32_e32 v200, v200, v201
	s_waitcnt lgkmcnt(5)
	v_mfma_f32_32x32x16_bf16 v[34:49], v[12:15], v[102:105], v[34:49]
	v_add_f32_e32 v203, v203, v206
	v_add_f32_e32 v204, v204, v186
	s_waitcnt lgkmcnt(4)
	v_mfma_f32_32x32x16_bf16 v[18:33], v[82:85], v[102:105], v[18:33]
	v_add_f32_e32 v187, v187, v112
	v_add_f32_e32 v205, v205, v110
	s_waitcnt lgkmcnt(0)
	v_mfma_f32_32x32x16_bf16 v[66:81], v[86:89], v[106:109], v[66:81]
	v_add_f32_e32 v185, v185, v16
	v_add_f32_e32 v199, v199, v200
	v_mfma_f32_32x32x16_bf16 v[50:65], v[90:93], v[106:109], v[50:65]
	v_add_f32_e32 v203, v203, v204
	v_add_f32_e32 v187, v187, v205
	v_mfma_f32_32x32x16_bf16 v[34:49], v[94:97], v[106:109], v[34:49]
	v_add_f32_e32 v185, v185, v199
	v_add_f32_e32 v203, v203, v187
	v_mfma_f32_32x32x16_bf16 v[18:33], v[98:101], v[106:109], v[18:33]
	v_add_f32_e32 v185, v185, v203
	v_add_f32_e32 v178, v178, v185

.LBB0_1025:
	s_lshl_b32 s0, s73, 14
	s_add_i32 s0, s0, 0x12000
	v_add_u32_e32 v2, s0, v163
	ds_read_b128 v[222:225], v2
	ds_read_b128 v[226:229], v2 offset:4096
	ds_read_b128 v[230:233], v2 offset:8192
	ds_read_b128 v[234:237], v2 offset:12288
	v_add_u32_e32 v2, s0, v171
	ds_read_b128 v[238:241], v2
	ds_read_b128 v[242:245], v2 offset:4096
	ds_read_b128 v[246:249], v2 offset:8192
	ds_read_b128 v[250:253], v2 offset:12288
	v_exp_f32_e32 v2, v98
	v_exp_f32_e32 v4, v99
	v_exp_f32_e32 v5, v100
	v_exp_f32_e32 v6, v101
	v_add_f32_e32 v7, 0, v2
	v_exp_f32_e32 v8, v102
	v_add_f32_e32 v7, v4, v7
	v_exp_f32_e32 v9, v103
	v_add_f32_e32 v7, v5, v7
	v_exp_f32_e32 v10, v104
	v_add_f32_e32 v7, v6, v7
	v_exp_f32_e32 v11, v105
	v_add_f32_e32 v7, v8, v7
	v_exp_f32_e32 v16, v106
	v_add_f32_e32 v7, v9, v7
	v_exp_f32_e32 v106, v107
	v_add_f32_e32 v7, v10, v7
	v_exp_f32_e32 v107, v108
	v_add_f32_e32 v7, v11, v7
	v_exp_f32_e32 v108, v109
	v_add_f32_e32 v7, v16, v7
	v_exp_f32_e32 v109, v110
	v_add_f32_e32 v7, v106, v7
	v_exp_f32_e32 v110, v111
	v_add_f32_e32 v7, v107, v7
	v_exp_f32_e32 v111, v112
	v_add_f32_e32 v7, v108, v7
	v_exp_f32_e32 v112, v113
	v_add_f32_e32 v7, v109, v7
	v_add_f32_e32 v7, v110, v7
	v_add_f32_e32 v7, v111, v7
	v_cvt_pk_bf16_f32 v4, v2, v4
	v_add_f32_e32 v17, v112, v7
	v_cvt_pk_bf16_f32 v5, v5, v6
	v_cvt_pk_bf16_f32 v6, v8, v9
	v_cvt_pk_bf16_f32 v7, v10, v11
	v_cvt_pk_bf16_f32 v106, v16, v106
	v_cvt_pk_bf16_f32 v107, v107, v108
	v_cvt_pk_bf16_f32 v108, v109, v110
	v_cvt_pk_bf16_f32 v109, v111, v112
	s_setprio 2
	s_waitcnt lgkmcnt(7)
	v_mfma_f32_32x32x16_bf16 v[66:81], v[222:225], v[4:7], v[66:81]
	v_exp_f32_e32 v2, v82
	v_exp_f32_e32 v179, v83
	s_nop 0
	v_add_f32_e32 v199, v2, v17
	s_waitcnt lgkmcnt(6)
	v_mfma_f32_32x32x16_bf16 v[50:65], v[226:229], v[4:7], v[50:65]
	v_exp_f32_e32 v192, v84
	v_exp_f32_e32 v16, v85
	s_waitcnt lgkmcnt(5)
	v_mfma_f32_32x32x16_bf16 v[34:49], v[230:233], v[4:7], v[34:49]
	v_exp_f32_e32 v17, v86
	v_exp_f32_e32 v193, v87
	s_waitcnt lgkmcnt(4)
	v_mfma_f32_32x32x16_bf16 v[18:33], v[234:237], v[4:7], v[18:33]
	v_exp_f32_e32 v196, v88
	v_exp_f32_e32 v194, v89
	v_add_u32_e32 v82, s0, v172
	ds_read_b128 v[4:7], v82
	ds_read_b128 v[8:11], v82 offset:4096
	ds_read_b128 v[12:15], v82 offset:8192
	ds_read_b128 v[82:85], v82 offset:12288
	s_waitcnt lgkmcnt(7)
	v_mfma_f32_32x32x16_bf16 v[66:81], v[238:241], v[106:109], v[66:81]
	v_exp_f32_e32 v195, v90
	v_exp_f32_e32 v197, v91
	s_waitcnt lgkmcnt(6)
	v_mfma_f32_32x32x16_bf16 v[50:65], v[242:245], v[106:109], v[50:65]
	v_exp_f32_e32 v200, v92
	v_exp_f32_e32 v198, v93
	s_waitcnt lgkmcnt(5)
	v_mfma_f32_32x32x16_bf16 v[34:49], v[246:249], v[106:109], v[34:49]
	v_exp_f32_e32 v180, v94
	v_exp_f32_e32 v181, v95
	s_waitcnt lgkmcnt(4)
	v_mfma_f32_32x32x16_bf16 v[18:33], v[250:253], v[106:109], v[18:33]
	v_exp_f32_e32 v112, v96
	v_exp_f32_e32 v110, v97
	v_add_u32_e32 v98, s0, v173
	ds_read_b128 v[86:89], v98
	ds_read_b128 v[90:93], v98 offset:4096
	ds_read_b128 v[94:97], v98 offset:8192
	ds_read_b128 v[98:101], v98 offset:12288
	v_cvt_pk_bf16_f32 v102, v2, v179
	v_cvt_pk_bf16_f32 v103, v192, v16
	v_cvt_pk_bf16_f32 v104, v17, v193
	v_cvt_pk_bf16_f32 v105, v196, v194
	v_cvt_pk_bf16_f32 v106, v195, v197
	v_cvt_pk_bf16_f32 v107, v200, v198
	v_cvt_pk_bf16_f32 v108, v180, v181
	v_cvt_pk_bf16_f32 v109, v112, v110
	s_waitcnt lgkmcnt(7)
	v_mfma_f32_32x32x16_bf16 v[66:81], v[4:7], v[102:105], v[66:81]
	v_add_f32_e32 v179, v179, v192
	v_add_f32_e32 v16, v16, v17
	s_waitcnt lgkmcnt(6)
	v_mfma_f32_32x32x16_bf16 v[50:65], v[8:11], v[102:105], v[50:65]
	v_add_f32_e32 v193, v193, v196
	v_add_f32_e32 v194, v194, v195
	s_waitcnt lgkmcnt(5)
	v_mfma_f32_32x32x16_bf16 v[34:49], v[12:15], v[102:105], v[34:49]
	v_add_f32_e32 v197, v197, v200
	v_add_f32_e32 v198, v198, v180
	s_waitcnt lgkmcnt(4)
	v_mfma_f32_32x32x16_bf16 v[18:33], v[82:85], v[102:105], v[18:33]
	v_add_f32_e32 v181, v181, v112
	v_add_f32_e32 v199, v199, v110
	s_waitcnt lgkmcnt(0)
	v_mfma_f32_32x32x16_bf16 v[66:81], v[86:89], v[106:109], v[66:81]
	v_add_f32_e32 v179, v179, v16
	v_add_f32_e32 v193, v193, v194
	v_mfma_f32_32x32x16_bf16 v[50:65], v[90:93], v[106:109], v[50:65]
	v_add_f32_e32 v197, v197, v198
	v_add_f32_e32 v181, v181, v199
	v_mfma_f32_32x32x16_bf16 v[34:49], v[94:97], v[106:109], v[34:49]
	v_add_f32_e32 v179, v179, v193
	v_add_f32_e32 v197, v197, v181
	v_mfma_f32_32x32x16_bf16 v[18:33], v[98:101], v[106:109], v[18:33]
	v_add_f32_e32 v179, v179, v197
	v_add_f32_e32 v178, v178, v179
